# rope table generation moved from workgroups 0-3 (slow half of prep) to workgroups 252-255
# baseline (speedup 1.0000x reference)
.LBB0_1460:
	s_or_b64 exec, exec, s[0:1]
	s_movk_i32 s0, 0x800
	v_add_u32_e32 v2, 0xfffe0800, v2
	v_cmp_gt_u32_e32 vcc, s0, v2
	s_and_saveexec_b64 s[0:1], vcc
	s_cbranch_execz .LBB0_1467
	v_and_b32_e32 v0, 31, v46
	v_cvt_f32_ubyte0_e32 v0, v0
	v_mul_f32_e32 v1, 0xbed49a78, v0
	s_mov_b32 s4, 0xc2fc0000
	v_cmp_gt_f32_e32 vcc, s4, v1
	v_mov_b32_e32 v1, 0x42800000
	s_add_u32 s4, s48, 0x8c9c000
	v_cndmask_b32_e32 v1, 0, v1, vcc
	v_fmac_f32_e32 v1, 0xbed49a78, v0
	v_exp_f32_e32 v0, v1
	v_cndmask_b32_e32 v1, 0, v170, vcc
	s_addc_u32 s5, s49, 0
	s_lshl_b32 s31, s92, 10
	v_ldexp_f32 v3, v0, v1
	v_lshlrev_b32_e32 v0, 1, v2
	s_nop 0
	s_mov_b64 s[24:25], 0
	s_branch .LBB0_1463
